# early buffer_wbl2 before every grid-barrier arrival atomic (v26 + 11 inserts)
# baseline (speedup 1.0000x reference)
; __device__ __forceinline__ unsigned xb_ld(unsigned* p)              { return __hip_atomic_load(p, __ATOMIC_RELAXED, __HIP_MEMORY_SCOPE_AGENT); }
; __device__ __forceinline__ unsigned xb_add(unsigned* p, unsigned v) { return __hip_atomic_fetch_add(p, v, __ATOMIC_RELAXED, __HIP_MEMORY_SCOPE_AGENT); }
; #define XB_SPIN(cond, bar) do { unsigned _sp = 0; while (cond) { __builtin_amdgcn_s_sleep(1); \
;     if ((++_sp & 255u) == 0u) { if (xb_ld(&(bar)[XB_TMO])) break; if (_sp > XB_SPIN_CAP) { atomicAdd(&(bar)[XB_TMO], 1u); break; } } } } while (0)
; __device__ __forceinline__ void xcd_barrier(const XcdBarrier& b) {
;     asm volatile("s_waitcnt vmcnt(0)" ::: "memory");
;     __syncthreads();
;     if (threadIdx.x == 0) {
;         unsigned* bar = b.bar;
;         __builtin_amdgcn_s_waitcnt(0);
;         unsigned nloc = b.st[0], nx = b.st[1];
;         if (nloc == 0u) { xcd_barrier_complete(bar, b.x, nloc, nx); b.st[0] = nloc; b.st[1] = nx; }
;         const unsigned old = xb_add(&bar[XB_XSUB(b.x)], 1u);
;         const unsigned gen = old / nloc;
;         if (old + 1u == (gen + 1u) * nloc) {
;             __builtin_amdgcn_fence(__ATOMIC_RELEASE, "agent");
;             asm volatile("s_waitcnt vmcnt(0)" ::: "memory");
;             const unsigned og = xb_add(&bar[XB_TOP], 1u);
;             const unsigned tg = og / nx;
;             if (og + 1u == (tg + 1u) * nx) xb_add(&bar[XB_TOPGEN], 1u);
;             else XB_SPIN(xb_ld(&bar[XB_TOPGEN]) == tg, bar);
.LBB0_38:
	s_mov_b64 s[40:41], exec
	s_lshl_b32 s2, s76, 8
	v_mbcnt_lo_u32_b32 v3, s40, 0
	s_add_u32 s8, s0, s2
	v_mbcnt_hi_u32_b32 v3, s41, v3
	s_addc_u32 s9, s1, 0
	v_cmp_eq_u32_e32 vcc, 0, v3
	s_and_saveexec_b64 s[42:43], vcc
	s_cbranch_execz .LBB0_40
	s_bcnt1_i32_b64 s2, s[40:41]
	v_mov_b32_e32 v5, 0x1000
	v_mov_b32_e32 v6, s2
	buffer_wbl2 sc1
	global_atomic_add v5, v5, v6, s[8:9] offset:1024 sc0

; __device__ __forceinline__ unsigned xb_add(unsigned* p, unsigned v) { return __hip_atomic_fetch_add(p, v, __ATOMIC_RELAXED, __HIP_MEMORY_SCOPE_AGENT); }
; __device__ __forceinline__ void xcd_barrier(const XcdBarrier& b) {
;     ...
;     if (threadIdx.x == 0) {
;         unsigned* bar = b.bar;
;         __builtin_amdgcn_s_waitcnt(0);
;         unsigned nloc = b.st[0], nx = b.st[1];
;         if (nloc == 0u) { xcd_barrier_complete(bar, b.x, nloc, nx); b.st[0] = nloc; b.st[1] = nx; }
;         const unsigned old = xb_add(&bar[XB_XSUB(b.x)], 1u);
;         const unsigned gen = old / nloc;
;         if (old + 1u == (gen + 1u) * nloc) {
;             __builtin_amdgcn_fence(__ATOMIC_RELEASE, "agent");
.LBB0_234:
	s_mov_b64 s[12:13], exec
	s_lshl_b32 s2, s4, 2
	v_mbcnt_lo_u32_b32 v3, s12, 0
	s_add_u32 s10, s0, s2
	v_mbcnt_hi_u32_b32 v3, s13, v3
	s_addc_u32 s11, s1, 0
	v_cmp_eq_u32_e32 vcc, 0, v3
	s_and_saveexec_b64 s[14:15], vcc
	s_cbranch_execz .LBB0_236
	s_bcnt1_i32_b64 s2, s[12:13]
	v_mov_b32_e32 v5, 0x1000
	v_mov_b32_e32 v6, s2
	buffer_wbl2 sc1
	global_atomic_add v5, v5, v6, s[10:11] offset:1024 sc0

; __device__ __forceinline__ unsigned xb_add(unsigned* p, unsigned v) { return __hip_atomic_fetch_add(p, v, __ATOMIC_RELAXED, __HIP_MEMORY_SCOPE_AGENT); }
; __device__ __forceinline__ void xcd_barrier(const XcdBarrier& b) {
;     ...
;     if (threadIdx.x == 0) {
;         unsigned* bar = b.bar;
;         __builtin_amdgcn_s_waitcnt(0);
;         unsigned nloc = b.st[0], nx = b.st[1];
;         if (nloc == 0u) { xcd_barrier_complete(bar, b.x, nloc, nx); b.st[0] = nloc; b.st[1] = nx; }
;         const unsigned old = xb_add(&bar[XB_XSUB(b.x)], 1u);
;         const unsigned gen = old / nloc;
;         if (old + 1u == (gen + 1u) * nloc) {
;             __builtin_amdgcn_fence(__ATOMIC_RELEASE, "agent");
.LBB0_567:
	s_mov_b64 s[6:7], exec
	v_mbcnt_lo_u32_b32 v3, s6, 0
	v_mbcnt_hi_u32_b32 v3, s7, v3
	v_cmp_eq_u32_e32 vcc, 0, v3
	s_and_saveexec_b64 s[4:5], vcc
	s_cbranch_execz .LBB0_569
	s_bcnt1_i32_b64 s2, s[6:7]
	v_mov_b32_e32 v5, s2
	v_readlane_b32 s2, v251, 5
	v_readlane_b32 s3, v251, 6
	s_nop 4
	buffer_wbl2 sc1
	global_atomic_add v5, v131, v5, s[2:3] sc0

; __device__ __forceinline__ unsigned xb_add(unsigned* p, unsigned v) { return __hip_atomic_fetch_add(p, v, __ATOMIC_RELAXED, __HIP_MEMORY_SCOPE_AGENT); }
; __device__ __forceinline__ void xcd_barrier(const XcdBarrier& b) {
;     ...
;     if (threadIdx.x == 0) {
;         unsigned* bar = b.bar;
;         __builtin_amdgcn_s_waitcnt(0);
;         unsigned nloc = b.st[0], nx = b.st[1];
;         if (nloc == 0u) { xcd_barrier_complete(bar, b.x, nloc, nx); b.st[0] = nloc; b.st[1] = nx; }
;         const unsigned old = xb_add(&bar[XB_XSUB(b.x)], 1u);
;         const unsigned gen = old / nloc;
;         if (old + 1u == (gen + 1u) * nloc) {
;             __builtin_amdgcn_fence(__ATOMIC_RELEASE, "agent");
.LBB0_715:
	s_mov_b64 s[6:7], exec
	v_mbcnt_lo_u32_b32 v3, s6, 0
	v_mbcnt_hi_u32_b32 v3, s7, v3
	v_cmp_eq_u32_e32 vcc, 0, v3
	s_and_saveexec_b64 s[4:5], vcc
	s_cbranch_execz .LBB0_717
	s_bcnt1_i32_b64 s3, s[6:7]
	v_readlane_b32 s6, v251, 5
	v_mov_b32_e32 v5, s3
	v_readlane_b32 s7, v251, 6
	s_nop 4
	buffer_wbl2 sc1
	global_atomic_add v5, v131, v5, s[6:7] sc0
